# prompt attention softmax: cross-half row max / row sum via v_permlane32_swap instead of ds_bpermute round trips
# speedup vs baseline: 1.0041x; 1.0041x over previous
.LBB0_2056:
	v_mov_b32_e32 v96, v101
	ds_read_b128 v[0:3], v135
	ds_read_b128 v[4:7], v135 offset:32
	s_load_dwordx2 s[0:1], s[40:41], 0x80
	s_add_i32 s39, s45, s38
	s_waitcnt lgkmcnt(0)
	v_mfma_f32_32x32x16_bf16 v[64:79], v[0:3], v[80:83], 0
	ds_read_b128 v[0:3], v135 offset:64
	s_add_u32 s0, s0, s36
	s_addc_u32 s1, s1, s37
	s_add_i32 s38, s38, 1
	s_nop 0
	v_mfma_f32_32x32x16_bf16 v[64:79], v[4:7], v[84:87], v[64:79]
	s_waitcnt lgkmcnt(0)
	v_mfma_f32_32x32x16_bf16 v[64:79], v[0:3], v[88:91], v[64:79]
	ds_read_b128 v[0:3], v135 offset:96
	s_waitcnt lgkmcnt(0)
	v_mfma_f32_32x32x16_bf16 v[64:79], v[0:3], v[92:95], v[64:79]
	ds_read_b128 v[0:3], v135 offset:4608
	s_waitcnt lgkmcnt(0)
	v_mfma_f32_32x32x16_bf16 v[48:63], v[0:3], v[80:83], 0
	ds_read_b128 v[0:3], v135 offset:4640
	s_waitcnt lgkmcnt(0)
	v_mfma_f32_32x32x16_bf16 v[48:63], v[0:3], v[84:87], v[48:63]
	ds_read_b128 v[0:3], v135 offset:4672
	s_waitcnt lgkmcnt(0)
	v_mfma_f32_32x32x16_bf16 v[48:63], v[0:3], v[88:91], v[48:63]
	ds_read_b128 v[0:3], v135 offset:4704
	s_waitcnt lgkmcnt(0)
	v_mfma_f32_32x32x16_bf16 v[48:63], v[0:3], v[92:95], v[48:63]
	ds_read_b128 v[0:3], v135 offset:9216
	s_waitcnt lgkmcnt(0)
	v_mfma_f32_32x32x16_bf16 v[32:47], v[0:3], v[80:83], 0
	ds_read_b128 v[0:3], v135 offset:9248
	s_waitcnt lgkmcnt(0)
	v_mfma_f32_32x32x16_bf16 v[32:47], v[0:3], v[84:87], v[32:47]
	ds_read_b128 v[0:3], v135 offset:9280
	s_waitcnt lgkmcnt(0)
	v_mfma_f32_32x32x16_bf16 v[32:47], v[0:3], v[88:91], v[32:47]
	ds_read_b128 v[0:3], v135 offset:9312
	s_waitcnt lgkmcnt(0)
	v_mfma_f32_32x32x16_bf16 v[32:47], v[0:3], v[92:95], v[32:47]
	ds_read_b128 v[0:3], v135 offset:13824
	s_waitcnt lgkmcnt(0)
	v_mfma_f32_32x32x16_bf16 v[16:31], v[0:3], v[80:83], 0
	ds_read_b128 v[0:3], v135 offset:13856
	s_waitcnt lgkmcnt(0)
	v_mfma_f32_32x32x16_bf16 v[16:31], v[0:3], v[84:87], v[16:31]
	ds_read_b128 v[0:3], v135 offset:13888
	s_waitcnt lgkmcnt(0)
	v_mfma_f32_32x32x16_bf16 v[16:31], v[0:3], v[88:91], v[16:31]
	ds_read_b128 v[0:3], v135 offset:13920
	s_waitcnt lgkmcnt(0)
	v_mfma_f32_32x32x16_bf16 v[16:31], v[0:3], v[92:95], v[16:31]
	ds_read_b128 v[0:3], v135 offset:18432
	s_waitcnt lgkmcnt(0)
	v_mfma_f32_32x32x16_bf16 v[0:15], v[0:3], v[80:83], 0
	ds_read_b128 v[80:83], v135 offset:18464
	s_waitcnt lgkmcnt(0)
	v_mfma_f32_32x32x16_bf16 v[0:15], v[80:83], v[84:87], v[0:15]
	ds_read_b128 v[80:83], v135 offset:18496
	s_waitcnt lgkmcnt(0)
	v_mfma_f32_32x32x16_bf16 v[0:15], v[80:83], v[88:91], v[0:15]
	ds_read_b128 v[80:83], v135 offset:18528
	s_waitcnt lgkmcnt(0)
	v_mfma_f32_32x32x16_bf16 v[0:15], v[80:83], v[92:95], v[0:15]
	global_load_dword v80, v97, s[0:1]
	v_add_u32_e32 v94, 0x80, v96
	v_cmp_le_i32_e64 s[0:1], v100, v96
	v_cmp_gt_i32_e32 vcc, v100, v94
	s_or_b64 s[0:1], s[0:1], vcc
	v_readlane_b32 vcc_lo, v254, 37
	v_readlane_b32 vcc_hi, v254, 38
	s_or_b64 vcc, s[0:1], vcc
	v_cmp_ge_i32_e64 s[0:1], v100, v94
	v_cndmask_b32_e32 v64, v64, v200, vcc
	v_cmp_lt_i32_e32 vcc, v100, v96
	s_or_b64 s[0:1], vcc, s[0:1]
	v_readlane_b32 vcc_lo, v254, 39
	v_readlane_b32 vcc_hi, v254, 40
	s_or_b64 vcc, s[0:1], vcc
	v_cmp_gt_i32_e64 s[0:1], v104, v94
	v_cndmask_b32_e32 v65, v65, v200, vcc
	v_cmp_le_i32_e32 vcc, v104, v96
	s_or_b64 s[0:1], vcc, s[0:1]
	v_readlane_b32 vcc_lo, v254, 20
	v_readlane_b32 vcc_hi, v254, 21
	s_or_b64 vcc, s[0:1], vcc
	v_cmp_gt_i32_e64 s[0:1], v105, v94
	v_cndmask_b32_e32 v66, v66, v200, vcc
	v_cmp_le_i32_e32 vcc, v105, v96
	s_or_b64 s[0:1], vcc, s[0:1]
	v_readlane_b32 vcc_lo, v254, 18
	v_readlane_b32 vcc_hi, v254, 19
	s_or_b64 vcc, s[0:1], vcc
	v_cmp_gt_i32_e64 s[0:1], v106, v94
	v_cndmask_b32_e32 v67, v67, v200, vcc
	v_cmp_le_i32_e32 vcc, v106, v96
	s_or_b64 s[0:1], vcc, s[0:1]
	v_readlane_b32 vcc_lo, v254, 41
	v_readlane_b32 vcc_hi, v254, 42
	s_or_b64 vcc, s[0:1], vcc
	v_cmp_gt_i32_e64 s[0:1], v107, v94
	v_cndmask_b32_e32 v68, v68, v200, vcc
	v_cmp_le_i32_e32 vcc, v107, v96
	s_or_b64 s[0:1], vcc, s[0:1]
	v_readlane_b32 vcc_lo, v254, 22
	v_readlane_b32 vcc_hi, v254, 23
	s_or_b64 vcc, s[0:1], vcc
	v_cmp_gt_i32_e64 s[0:1], v108, v94
	v_cndmask_b32_e32 v69, v69, v200, vcc
	v_cmp_le_i32_e32 vcc, v108, v96
	s_or_b64 s[0:1], vcc, s[0:1]
	v_readlane_b32 vcc_lo, v254, 24
	v_readlane_b32 vcc_hi, v254, 25
	s_or_b64 vcc, s[0:1], vcc
	v_cmp_gt_i32_e64 s[0:1], v109, v94
	v_cndmask_b32_e32 v70, v70, v200, vcc
	v_cmp_le_i32_e32 vcc, v109, v96
	s_or_b64 s[0:1], vcc, s[0:1]
	v_readlane_b32 vcc_lo, v254, 26
	v_readlane_b32 vcc_hi, v254, 27
	s_or_b64 vcc, s[0:1], vcc
	v_cmp_gt_i32_e64 s[0:1], v110, v94
	v_cndmask_b32_e32 v71, v71, v200, vcc
	v_cmp_le_i32_e32 vcc, v110, v96
	s_or_b64 s[0:1], vcc, s[0:1]
	v_readlane_b32 vcc_lo, v254, 28
	v_readlane_b32 vcc_hi, v254, 29
	s_or_b64 vcc, s[0:1], vcc
	v_cmp_gt_i32_e64 s[0:1], v111, v94
	v_cndmask_b32_e32 v72, v72, v200, vcc
	v_cmp_le_i32_e32 vcc, v111, v96
	s_or_b64 s[0:1], vcc, s[0:1]
	v_readlane_b32 vcc_lo, v254, 32
	v_readlane_b32 vcc_hi, v254, 33
	s_or_b64 vcc, s[0:1], vcc
	v_cmp_gt_i32_e64 s[0:1], v112, v94
	v_cndmask_b32_e32 v73, v73, v200, vcc
	v_cmp_le_i32_e32 vcc, v112, v96
	s_or_b64 s[0:1], vcc, s[0:1]
	v_readlane_b32 vcc_lo, v254, 34
	v_readlane_b32 vcc_hi, v254, 35
	s_or_b64 vcc, s[0:1], vcc
	v_cmp_gt_i32_e64 s[0:1], v113, v94
	v_cndmask_b32_e32 v74, v74, v200, vcc
	v_cmp_le_i32_e32 vcc, v113, v96
	s_or_b64 s[0:1], vcc, s[0:1]
	v_readlane_b32 vcc_lo, v254, 5
	v_readlane_b32 vcc_hi, v254, 6
	s_or_b64 vcc, s[0:1], vcc
	v_cmp_gt_i32_e64 s[0:1], v114, v94
	v_cndmask_b32_e32 v75, v75, v200, vcc
	v_cmp_le_i32_e32 vcc, v114, v96
	s_or_b64 s[0:1], vcc, s[0:1]
	v_readlane_b32 vcc_lo, v254, 8
	v_readlane_b32 vcc_hi, v254, 9
	s_or_b64 vcc, s[0:1], vcc
	v_cmp_gt_i32_e64 s[0:1], v115, v94
	v_cndmask_b32_e32 v76, v76, v200, vcc
	v_cmp_le_i32_e32 vcc, v115, v96
	s_or_b64 s[0:1], vcc, s[0:1]
	v_readlane_b32 vcc_lo, v254, 30
	v_readlane_b32 vcc_hi, v254, 31
	s_or_b64 vcc, s[0:1], vcc
	v_cmp_gt_i32_e64 s[0:1], v116, v94
	v_cndmask_b32_e32 v77, v77, v200, vcc
	v_cmp_le_i32_e32 vcc, v116, v96
	s_or_b64 s[0:1], vcc, s[0:1]
	v_readlane_b32 vcc_lo, v254, 58
	v_readlane_b32 vcc_hi, v254, 59
	s_or_b64 vcc, s[0:1], vcc
	v_cmp_gt_i32_e64 s[0:1], v117, v94
	v_cndmask_b32_e32 v85, v78, v200, vcc
	v_cmp_le_i32_e32 vcc, v117, v96
	s_or_b64 s[0:1], vcc, s[0:1]
	v_readlane_b32 vcc_lo, v254, 60
	v_readlane_b32 vcc_hi, v254, 61
	s_or_b64 vcc, s[0:1], vcc
	v_readlane_b32 s0, v254, 62
	v_readlane_b32 s1, v254, 63
	s_waitcnt vmcnt(0)
	v_max3_f32 v81, v80, v64, v65
	v_max3_f32 v81, v81, v66, v67
	v_cndmask_b32_e64 v93, v48, v200, s[0:1]
	v_readlane_b32 s0, v255, 0
	v_readlane_b32 s1, v255, 1
	v_max3_f32 v81, v81, v68, v69
	v_max3_f32 v81, v81, v70, v71
	v_cndmask_b32_e64 v90, v49, v200, s[0:1]
	v_readlane_b32 s0, v255, 2
	v_readlane_b32 s1, v255, 3
	v_max3_f32 v81, v81, v72, v73
	v_max3_f32 v81, v81, v74, v75
	v_cndmask_b32_e64 v91, v50, v200, s[0:1]
	v_readlane_b32 s0, v255, 4
	v_readlane_b32 s1, v255, 5
	v_max3_f32 v81, v81, v76, v77
	v_cndmask_b32_e32 v92, v79, v200, vcc
	v_cndmask_b32_e64 v88, v51, v200, s[0:1]
	v_readlane_b32 s0, v255, 6
	v_readlane_b32 s1, v255, 7
	v_max3_f32 v78, v81, v85, v92
	v_max3_f32 v48, v78, v93, v90
	v_cndmask_b32_e64 v89, v52, v200, s[0:1]
	v_readlane_b32 s0, v255, 8
	v_readlane_b32 s1, v255, 9
	v_cmp_le_i32_e32 vcc, v118, v96
	v_max3_f32 v48, v48, v91, v88
	v_cndmask_b32_e64 v86, v53, v200, s[0:1]
	v_readlane_b32 s0, v255, 10
	v_readlane_b32 s1, v255, 11
	v_max3_f32 v48, v48, v89, v86
	v_cndmask_b32_e64 v52, v39, v200, s[6:7]
	v_cndmask_b32_e64 v87, v54, v200, s[0:1]
	v_readlane_b32 s0, v255, 12
	v_readlane_b32 s1, v255, 13
	v_cndmask_b32_e64 v51, v40, v200, s[50:51]
	v_cndmask_b32_e64 v50, v41, v200, s[52:53]
	v_cndmask_b32_e64 v83, v55, v200, s[0:1]
	v_readlane_b32 s0, v255, 14
	v_readlane_b32 s1, v255, 15
	v_max3_f32 v48, v48, v87, v83
	v_cndmask_b32_e64 v49, v42, v200, s[54:55]
	v_cndmask_b32_e64 v84, v56, v200, s[0:1]
	v_readlane_b32 s0, v255, 16
	v_readlane_b32 s1, v255, 17
	v_cndmask_b32_e64 v42, v45, v200, s[60:61]
	v_cndmask_b32_e64 v41, v46, v200, s[62:63]
	v_cndmask_b32_e64 v81, v57, v200, s[0:1]
	v_readlane_b32 s0, v255, 18
	v_readlane_b32 s1, v255, 19
	v_max3_f32 v48, v48, v84, v81
	v_cndmask_b32_e64 v40, v47, v200, s[64:65]
	v_cndmask_b32_e64 v82, v58, v200, s[0:1]
	v_readlane_b32 s0, v255, 20
	v_readlane_b32 s1, v255, 21
	v_cndmask_b32_e64 v39, v16, v200, s[66:67]
	s_nop 0
	v_cndmask_b32_e64 v78, v59, v200, s[0:1]
	v_readlane_b32 s0, v255, 22
	v_readlane_b32 s1, v255, 23
	v_max3_f32 v48, v48, v82, v78
	s_nop 0
	v_cndmask_b32_e64 v79, v60, v200, s[0:1]
	v_readlane_b32 s0, v255, 24
	v_readlane_b32 s1, v255, 25
	s_nop 1
	v_cndmask_b32_e64 v61, v61, v200, s[0:1]
	v_readlane_b32 s0, v255, 26
	v_readlane_b32 s1, v255, 27
	v_max3_f32 v48, v48, v79, v61
	s_nop 0
	v_cndmask_b32_e64 v62, v62, v200, s[0:1]
	v_readlane_b32 s0, v255, 28
	v_readlane_b32 s1, v255, 29
	s_nop 1
	v_cndmask_b32_e64 v59, v63, v200, s[0:1]
	v_readlane_b32 s0, v255, 30
	v_readlane_b32 s1, v255, 31
	v_max3_f32 v48, v48, v62, v59
	s_nop 0
	v_cndmask_b32_e64 v60, v32, v200, s[0:1]
	v_readlane_b32 s0, v255, 32
	v_readlane_b32 s1, v255, 33
	s_nop 1
	v_cndmask_b32_e64 v57, v33, v200, s[0:1]
	v_readlane_b32 s0, v255, 34
	v_readlane_b32 s1, v255, 35
	v_max3_f32 v32, v48, v60, v57
	v_cndmask_b32_e64 v48, v43, v200, s[56:57]
	v_cndmask_b32_e64 v58, v34, v200, s[0:1]
	v_readlane_b32 s0, v255, 36
	v_readlane_b32 s1, v255, 37
	v_cndmask_b32_e64 v43, v44, v200, s[58:59]
	v_cndmask_b32_e64 v34, v21, v200, s[76:77]
	v_cndmask_b32_e64 v55, v35, v200, s[0:1]
	v_readlane_b32 s0, v255, 38
	v_readlane_b32 s1, v255, 39
	v_max3_f32 v32, v32, v58, v55
	v_cndmask_b32_e64 v35, v20, v200, s[74:75]
	v_cndmask_b32_e64 v56, v36, v200, s[0:1]
	v_readlane_b32 s0, v255, 40
	v_readlane_b32 s1, v255, 41
	v_cndmask_b32_e64 v36, v19, v200, s[72:73]
	v_cndmask_b32_e64 v33, v22, v200, s[78:79]
	v_cndmask_b32_e64 v53, v37, v200, s[0:1]
	v_readlane_b32 s0, v255, 42
	v_readlane_b32 s1, v255, 43
	v_max3_f32 v32, v32, v56, v53
	v_cndmask_b32_e64 v37, v18, v200, s[70:71]
	v_cndmask_b32_e64 v54, v38, v200, s[0:1]
	v_cmp_gt_i32_e64 s[0:1], v100, v96
	s_or_b64 s[0:1], vcc, s[0:1]
	s_or_b64 vcc, s[0:1], s[42:43]
	v_cndmask_b32_e32 v0, v0, v200, vcc
	v_cmp_le_i32_e32 vcc, v119, v96
	v_cmp_gt_i32_e64 s[0:1], v119, v94
	s_or_b64 s[0:1], vcc, s[0:1]
	s_or_b64 vcc, s[0:1], s[4:5]
	v_cndmask_b32_e32 v1, v1, v200, vcc
	v_cmp_le_i32_e32 vcc, v120, v96
	v_cmp_gt_i32_e64 s[0:1], v120, v94
	s_or_b64 s[0:1], vcc, s[0:1]
	s_or_b64 vcc, s[0:1], s[48:49]
	v_cndmask_b32_e32 v2, v2, v200, vcc
	v_cmp_le_i32_e32 vcc, v121, v96
	v_cmp_gt_i32_e64 s[0:1], v121, v94
	s_or_b64 s[0:1], vcc, s[0:1]
	s_or_b64 vcc, s[0:1], s[8:9]
	v_cndmask_b32_e32 v3, v3, v200, vcc
	v_cmp_le_i32_e32 vcc, v122, v96
	v_cmp_gt_i32_e64 s[0:1], v122, v94
	s_or_b64 s[0:1], vcc, s[0:1]
	s_or_b64 vcc, s[0:1], s[10:11]
	v_cndmask_b32_e32 v4, v4, v200, vcc
	v_cmp_le_i32_e32 vcc, v123, v96
	v_cmp_gt_i32_e64 s[0:1], v123, v94
	s_or_b64 s[0:1], vcc, s[0:1]
	s_or_b64 vcc, s[0:1], s[12:13]
	v_cndmask_b32_e32 v5, v5, v200, vcc
	v_cmp_le_i32_e32 vcc, v124, v96
	v_cmp_gt_i32_e64 s[0:1], v124, v94
	s_or_b64 s[0:1], vcc, s[0:1]
	s_or_b64 vcc, s[0:1], s[14:15]
	v_cndmask_b32_e32 v6, v6, v200, vcc
	v_cmp_le_i32_e32 vcc, v125, v96
	v_cmp_gt_i32_e64 s[0:1], v125, v94
	s_or_b64 s[0:1], vcc, s[0:1]
	s_or_b64 vcc, s[0:1], s[16:17]
	v_cndmask_b32_e32 v7, v7, v200, vcc
	v_cmp_le_i32_e32 vcc, v126, v96
	v_cmp_gt_i32_e64 s[0:1], v126, v94
	s_or_b64 s[0:1], vcc, s[0:1]
	s_or_b64 vcc, s[0:1], s[18:19]
	v_cndmask_b32_e32 v8, v8, v200, vcc
	v_cmp_le_i32_e32 vcc, v127, v96
	v_cmp_gt_i32_e64 s[0:1], v127, v94
	s_or_b64 s[0:1], vcc, s[0:1]
	s_or_b64 vcc, s[0:1], s[20:21]
	v_max3_f32 v32, v32, v54, v52
	v_cndmask_b32_e32 v9, v9, v200, vcc
	v_cmp_le_i32_e32 vcc, v128, v96
	v_cmp_gt_i32_e64 s[0:1], v128, v94
	v_max3_f32 v32, v32, v51, v50
	s_or_b64 s[0:1], vcc, s[0:1]
	v_max3_f32 v32, v32, v49, v48
	s_or_b64 vcc, s[0:1], s[22:23]
	v_max3_f32 v32, v32, v43, v42
	v_cndmask_b32_e32 v10, v10, v200, vcc
	v_cmp_le_i32_e32 vcc, v129, v96
	v_cmp_gt_i32_e64 s[0:1], v129, v94
	v_max3_f32 v32, v32, v41, v40
	v_cndmask_b32_e64 v38, v17, v200, s[68:69]
	s_or_b64 s[0:1], vcc, s[0:1]
	v_max3_f32 v16, v32, v39, v38
	s_or_b64 vcc, s[0:1], s[24:25]
	v_max3_f32 v16, v16, v37, v36
	v_cndmask_b32_e32 v11, v11, v200, vcc
	v_cmp_le_i32_e32 vcc, v130, v96
	v_cmp_gt_i32_e64 s[0:1], v130, v94
	v_max3_f32 v16, v16, v35, v34
	v_cndmask_b32_e64 v32, v23, v200, s[80:81]
	s_or_b64 s[0:1], vcc, s[0:1]
	v_max3_f32 v16, v16, v33, v32
	v_cndmask_b32_e64 v23, v24, v200, s[82:83]
	v_cndmask_b32_e64 v22, v25, v200, s[84:85]
	s_or_b64 vcc, s[0:1], s[26:27]
	v_max3_f32 v16, v16, v23, v22
	v_cndmask_b32_e64 v21, v26, v200, s[86:87]
	v_cndmask_b32_e64 v20, v27, v200, s[88:89]
	v_cndmask_b32_e32 v12, v12, v200, vcc
	v_cmp_le_i32_e32 vcc, v131, v96
	v_cmp_gt_i32_e64 s[0:1], v131, v94
	v_max3_f32 v16, v16, v21, v20
	v_cndmask_b32_e64 v19, v28, v200, s[90:91]
	v_cndmask_b32_e64 v18, v29, v200, s[92:93]
	s_or_b64 s[0:1], vcc, s[0:1]
	v_max3_f32 v24, v16, v19, v18
	v_cndmask_b32_e64 v17, v30, v200, s[94:95]
	v_cndmask_b32_e64 v16, v31, v200, s[96:97]
	s_or_b64 vcc, s[0:1], s[28:29]
	v_max3_f32 v24, v24, v17, v16
	v_cndmask_b32_e32 v13, v13, v200, vcc
	v_cmp_le_i32_e32 vcc, v132, v96
	v_cmp_gt_i32_e64 s[0:1], v132, v94
	v_max3_f32 v24, v24, v0, v1
	s_or_b64 s[0:1], vcc, s[0:1]
	v_max3_f32 v24, v24, v2, v3
	s_or_b64 vcc, s[0:1], s[30:31]
	v_max3_f32 v24, v24, v4, v5
	v_cndmask_b32_e32 v14, v14, v200, vcc
	v_cmp_le_i32_e32 vcc, v133, v96
	v_cmp_gt_i32_e64 s[0:1], v133, v94
	v_max3_f32 v24, v24, v6, v7
	s_or_b64 s[0:1], vcc, s[0:1]
	v_and_b32_e32 v26, 64, v198
	v_max3_f32 v24, v24, v8, v9
	s_or_b64 vcc, s[0:1], s[34:35]
	v_xor_b32_e32 v25, 32, v198
	v_add_u32_e32 v26, 64, v26
	v_max3_f32 v24, v24, v10, v11
	v_cndmask_b32_e32 v15, v15, v200, vcc
	v_cmp_lt_i32_e32 vcc, v25, v26
	v_max3_f32 v24, v24, v12, v13
	v_max3_f32 v24, v24, v14, v15
	v_cndmask_b32_e32 v25, v198, v25, vcc
	v_lshlrev_b32_e32 v25, 2, v25
	v_mov_b32_e32 v26, v24
	v_mov_b32_e32 v226, v24
	s_nop 1
	v_permlane32_swap_b32_e32 v26, v226
	s_lshr_b32 s1, s39, 2
	s_mulk_i32 s1, 0x4080
	s_add_i32 s2, s1, 0x20400
	s_add_i32 s0, s44, s33
	s_waitcnt lgkmcnt(0)
	v_max_f32_e32 v24, v26, v226
	v_sub_f32_e32 v26, v64, v24
	v_mul_f32_e32 v26, 0x3fb8aa3b, v26
	v_sub_f32_e32 v28, v65, v24
	v_exp_f32_e32 v26, v26
	v_mul_f32_e32 v28, 0x3fb8aa3b, v28
	v_sub_f32_e32 v29, v66, v24
	v_exp_f32_e32 v28, v28
	v_mul_f32_e32 v29, 0x3fb8aa3b, v29
	v_sub_f32_e32 v30, v67, v24
	v_exp_f32_e32 v29, v29
	v_mul_f32_e32 v30, 0x3fb8aa3b, v30
	v_sub_f32_e32 v31, v68, v24
	v_exp_f32_e32 v30, v30
	v_mul_f32_e32 v31, 0x3fb8aa3b, v31
	v_sub_f32_e32 v44, v69, v24
	v_add_f32_e32 v27, 0, v26
	v_exp_f32_e32 v31, v31
	v_mul_f32_e32 v44, 0x3fb8aa3b, v44
	v_sub_f32_e32 v45, v70, v24
	v_add_f32_e32 v27, v28, v27
	v_exp_f32_e32 v44, v44
	v_mul_f32_e32 v45, 0x3fb8aa3b, v45
	v_sub_f32_e32 v46, v71, v24
	v_add_f32_e32 v27, v29, v27
	v_exp_f32_e32 v45, v45
	v_mul_f32_e32 v46, 0x3fb8aa3b, v46
	v_sub_f32_e32 v47, v72, v24
	v_add_f32_e32 v27, v30, v27
	v_exp_f32_e32 v46, v46
	v_mul_f32_e32 v47, 0x3fb8aa3b, v47
	v_sub_f32_e32 v63, v73, v24
	v_add_f32_e32 v27, v31, v27
	v_exp_f32_e32 v47, v47
	v_mul_f32_e32 v63, 0x3fb8aa3b, v63
	v_sub_f32_e32 v64, v74, v24
	v_add_f32_e32 v27, v44, v27
	v_exp_f32_e32 v63, v63
	v_mul_f32_e32 v64, 0x3fb8aa3b, v64
	v_sub_f32_e32 v65, v75, v24
	v_add_f32_e32 v27, v45, v27
	v_exp_f32_e32 v64, v64
	v_mul_f32_e32 v65, 0x3fb8aa3b, v65
	v_sub_f32_e32 v66, v76, v24
	v_add_f32_e32 v27, v46, v27
	v_exp_f32_e32 v65, v65
	v_mul_f32_e32 v66, 0x3fb8aa3b, v66
	v_sub_f32_e32 v67, v77, v24
	v_add_f32_e32 v27, v47, v27
	v_exp_f32_e32 v66, v66
	v_mul_f32_e32 v67, 0x3fb8aa3b, v67
	v_sub_f32_e32 v68, v85, v24
	v_add_f32_e32 v27, v63, v27
	v_exp_f32_e32 v67, v67
	v_mul_f32_e32 v68, 0x3fb8aa3b, v68
	v_sub_f32_e32 v69, v92, v24
	v_add_f32_e32 v27, v64, v27
	v_exp_f32_e32 v68, v68
	v_mul_f32_e32 v69, 0x3fb8aa3b, v69
	v_sub_f32_e32 v70, v93, v24
	v_add_f32_e32 v27, v65, v27
	v_exp_f32_e32 v69, v69
	v_mul_f32_e32 v70, 0x3fb8aa3b, v70
	v_sub_f32_e32 v71, v90, v24
	v_add_f32_e32 v27, v66, v27
	v_exp_f32_e32 v70, v70
	v_mul_f32_e32 v71, 0x3fb8aa3b, v71
	v_sub_f32_e32 v72, v91, v24
	v_add_f32_e32 v27, v67, v27
	v_exp_f32_e32 v71, v71
	v_mul_f32_e32 v72, 0x3fb8aa3b, v72
	v_sub_f32_e32 v73, v88, v24
	v_add_f32_e32 v27, v68, v27
	v_exp_f32_e32 v72, v72
	v_mul_f32_e32 v73, 0x3fb8aa3b, v73
	v_sub_f32_e32 v74, v89, v24
	v_add_f32_e32 v27, v69, v27
	v_exp_f32_e32 v73, v73
	v_mul_f32_e32 v74, 0x3fb8aa3b, v74
	v_sub_f32_e32 v75, v86, v24
	v_add_f32_e32 v27, v70, v27
	v_exp_f32_e32 v74, v74
	v_mul_f32_e32 v75, 0x3fb8aa3b, v75
	v_sub_f32_e32 v76, v87, v24
	v_add_f32_e32 v27, v71, v27
	v_exp_f32_e32 v75, v75
	v_mul_f32_e32 v76, 0x3fb8aa3b, v76
	v_sub_f32_e32 v77, v83, v24
	v_add_f32_e32 v27, v72, v27
	v_exp_f32_e32 v76, v76
	v_mul_f32_e32 v77, 0x3fb8aa3b, v77
	v_sub_f32_e32 v83, v84, v24
	v_add_f32_e32 v27, v73, v27
	v_exp_f32_e32 v77, v77
	v_mul_f32_e32 v83, 0x3fb8aa3b, v83
	v_sub_f32_e32 v81, v81, v24
	v_add_f32_e32 v27, v74, v27
	v_exp_f32_e32 v83, v83
	v_mul_f32_e32 v81, 0x3fb8aa3b, v81
	v_sub_f32_e32 v82, v82, v24
	v_add_f32_e32 v27, v75, v27
	v_exp_f32_e32 v81, v81
	v_mul_f32_e32 v82, 0x3fb8aa3b, v82
	v_sub_f32_e32 v78, v78, v24
	v_add_f32_e32 v27, v76, v27
	v_exp_f32_e32 v82, v82
	v_mul_f32_e32 v78, 0x3fb8aa3b, v78
	v_sub_f32_e32 v79, v79, v24
	v_add_f32_e32 v27, v77, v27
	v_exp_f32_e32 v78, v78
	v_mul_f32_e32 v79, 0x3fb8aa3b, v79
	v_sub_f32_e32 v61, v61, v24
	v_add_f32_e32 v27, v83, v27
	v_exp_f32_e32 v79, v79
	v_mul_f32_e32 v61, 0x3fb8aa3b, v61
	v_sub_f32_e32 v62, v62, v24
	v_add_f32_e32 v27, v81, v27
	v_exp_f32_e32 v61, v61
	v_mul_f32_e32 v62, 0x3fb8aa3b, v62
	v_sub_f32_e32 v59, v59, v24
	v_add_f32_e32 v27, v82, v27
	v_exp_f32_e32 v62, v62
	v_mul_f32_e32 v59, 0x3fb8aa3b, v59
	v_sub_f32_e32 v60, v60, v24
	v_add_f32_e32 v27, v78, v27
	v_exp_f32_e32 v59, v59
	v_mul_f32_e32 v60, 0x3fb8aa3b, v60
	v_sub_f32_e32 v57, v57, v24
	v_add_f32_e32 v27, v79, v27
	v_exp_f32_e32 v60, v60
	v_mul_f32_e32 v57, 0x3fb8aa3b, v57
	v_sub_f32_e32 v58, v58, v24
	v_add_f32_e32 v27, v61, v27
	v_exp_f32_e32 v57, v57
	v_mul_f32_e32 v58, 0x3fb8aa3b, v58
	v_sub_f32_e32 v55, v55, v24
	v_add_f32_e32 v27, v62, v27
	v_exp_f32_e32 v58, v58
	v_mul_f32_e32 v55, 0x3fb8aa3b, v55
	v_sub_f32_e32 v56, v56, v24
	v_add_f32_e32 v27, v59, v27
	v_exp_f32_e32 v55, v55
	v_mul_f32_e32 v56, 0x3fb8aa3b, v56
	v_sub_f32_e32 v53, v53, v24
	v_add_f32_e32 v27, v60, v27
	v_exp_f32_e32 v56, v56
	v_mul_f32_e32 v53, 0x3fb8aa3b, v53
	v_sub_f32_e32 v54, v54, v24
	v_add_f32_e32 v27, v57, v27
	v_exp_f32_e32 v53, v53
	v_mul_f32_e32 v54, 0x3fb8aa3b, v54
	v_sub_f32_e32 v52, v52, v24
	v_add_f32_e32 v27, v58, v27
	v_exp_f32_e32 v54, v54
	v_mul_f32_e32 v52, 0x3fb8aa3b, v52
	v_sub_f32_e32 v51, v51, v24
	v_add_f32_e32 v27, v55, v27
	v_exp_f32_e32 v52, v52
	v_mul_f32_e32 v51, 0x3fb8aa3b, v51
	v_sub_f32_e32 v50, v50, v24
	v_add_f32_e32 v27, v56, v27
	v_exp_f32_e32 v51, v51
	v_mul_f32_e32 v50, 0x3fb8aa3b, v50
	v_sub_f32_e32 v49, v49, v24
	v_add_f32_e32 v27, v53, v27
	v_exp_f32_e32 v50, v50
	v_mul_f32_e32 v49, 0x3fb8aa3b, v49
	v_sub_f32_e32 v48, v48, v24
	v_add_f32_e32 v27, v54, v27
	v_exp_f32_e32 v49, v49
	v_mul_f32_e32 v48, 0x3fb8aa3b, v48
	v_sub_f32_e32 v43, v43, v24
	v_add_f32_e32 v27, v52, v27
	v_exp_f32_e32 v48, v48
	v_mul_f32_e32 v43, 0x3fb8aa3b, v43
	v_sub_f32_e32 v42, v42, v24
	v_add_f32_e32 v27, v51, v27
	v_exp_f32_e32 v84, v43
	v_mul_f32_e32 v42, 0x3fb8aa3b, v42
	v_sub_f32_e32 v41, v41, v24
	v_add_f32_e32 v27, v50, v27
	v_exp_f32_e32 v85, v42
	v_mul_f32_e32 v41, 0x3fb8aa3b, v41
	v_sub_f32_e32 v40, v40, v24
	v_add_f32_e32 v27, v49, v27
	v_exp_f32_e32 v86, v41
	v_mul_f32_e32 v40, 0x3fb8aa3b, v40
	v_sub_f32_e32 v39, v39, v24
	v_add_f32_e32 v27, v48, v27
	v_exp_f32_e32 v87, v40
	v_mul_f32_e32 v39, 0x3fb8aa3b, v39
	v_sub_f32_e32 v38, v38, v24
	v_add_f32_e32 v27, v84, v27
	v_exp_f32_e32 v88, v39
	v_mul_f32_e32 v38, 0x3fb8aa3b, v38
	v_sub_f32_e32 v37, v37, v24
	v_add_f32_e32 v27, v85, v27
	v_exp_f32_e32 v89, v38
	v_mul_f32_e32 v37, 0x3fb8aa3b, v37
	v_sub_f32_e32 v36, v36, v24
	v_sub_f32_e32 v1, v1, v24
	v_add_f32_e32 v27, v86, v27
	v_exp_f32_e32 v90, v37
	v_mul_f32_e32 v36, 0x3fb8aa3b, v36
	v_sub_f32_e32 v35, v35, v24
	v_mul_f32_e32 v1, 0x3fb8aa3b, v1
	v_add_f32_e32 v27, v87, v27
	v_exp_f32_e32 v91, v36
	v_mul_f32_e32 v35, 0x3fb8aa3b, v35
	v_sub_f32_e32 v34, v34, v24
	v_exp_f32_e32 v142, v1
	v_sub_f32_e32 v1, v2, v24
	v_add_f32_e32 v27, v88, v27
	v_exp_f32_e32 v35, v35
	v_mul_f32_e32 v34, 0x3fb8aa3b, v34
	v_sub_f32_e32 v33, v33, v24
	v_mul_f32_e32 v1, 0x3fb8aa3b, v1
	v_add_f32_e32 v27, v89, v27
	v_exp_f32_e32 v92, v34
	v_mul_f32_e32 v33, 0x3fb8aa3b, v33
	v_sub_f32_e32 v32, v32, v24
	v_exp_f32_e32 v143, v1
	v_sub_f32_e32 v1, v3, v24
	v_add_f32_e32 v27, v90, v27
	v_exp_f32_e32 v33, v33
	v_mul_f32_e32 v32, 0x3fb8aa3b, v32
	v_sub_f32_e32 v23, v23, v24
	v_mul_f32_e32 v1, 0x3fb8aa3b, v1
	v_add_f32_e32 v27, v91, v27
	v_exp_f32_e32 v32, v32
	v_mul_f32_e32 v23, 0x3fb8aa3b, v23
	v_sub_f32_e32 v22, v22, v24
	v_exp_f32_e32 v144, v1
	v_sub_f32_e32 v1, v4, v24
	v_add_f32_e32 v27, v35, v27
	v_exp_f32_e32 v93, v23
	v_mul_f32_e32 v22, 0x3fb8aa3b, v22
	v_sub_f32_e32 v21, v21, v24
	v_mul_f32_e32 v1, 0x3fb8aa3b, v1
	v_add_f32_e32 v27, v92, v27
	v_exp_f32_e32 v94, v22
	v_mul_f32_e32 v21, 0x3fb8aa3b, v21
	v_sub_f32_e32 v20, v20, v24
	v_exp_f32_e32 v145, v1
	v_sub_f32_e32 v1, v5, v24
	v_add_f32_e32 v27, v33, v27
	v_exp_f32_e32 v95, v21
	v_mul_f32_e32 v20, 0x3fb8aa3b, v20
	v_sub_f32_e32 v19, v19, v24
	v_mul_f32_e32 v1, 0x3fb8aa3b, v1
	v_add_f32_e32 v27, v32, v27
	v_exp_f32_e32 v96, v20
	v_mul_f32_e32 v19, 0x3fb8aa3b, v19
	v_sub_f32_e32 v18, v18, v24
	v_exp_f32_e32 v146, v1
	v_sub_f32_e32 v1, v6, v24
	v_add_f32_e32 v23, v93, v27
	v_exp_f32_e32 v137, v19
	v_mul_f32_e32 v18, 0x3fb8aa3b, v18
	v_sub_f32_e32 v17, v17, v24
	v_mul_f32_e32 v1, 0x3fb8aa3b, v1
	v_add_f32_e32 v22, v94, v23
	v_exp_f32_e32 v138, v18
	v_mul_f32_e32 v17, 0x3fb8aa3b, v17
	v_sub_f32_e32 v16, v16, v24
	v_exp_f32_e32 v147, v1
	v_sub_f32_e32 v1, v7, v24
	v_add_f32_e32 v21, v95, v22
	v_exp_f32_e32 v139, v17
	v_mul_f32_e32 v16, 0x3fb8aa3b, v16
	v_sub_f32_e32 v0, v0, v24
	v_mul_f32_e32 v1, 0x3fb8aa3b, v1
	v_add_f32_e32 v20, v96, v21
	v_exp_f32_e32 v140, v16
	v_mul_f32_e32 v0, 0x3fb8aa3b, v0
	v_exp_f32_e32 v148, v1
	v_sub_f32_e32 v1, v8, v24
	v_add_f32_e32 v19, v137, v20
	v_exp_f32_e32 v141, v0
	v_mul_f32_e32 v1, 0x3fb8aa3b, v1
	v_add_f32_e32 v18, v138, v19
	v_exp_f32_e32 v149, v1
	v_sub_f32_e32 v1, v9, v24
	v_add_f32_e32 v17, v139, v18
	v_mul_f32_e32 v1, 0x3fb8aa3b, v1
	v_add_f32_e32 v16, v140, v17
	v_exp_f32_e32 v150, v1
	v_sub_f32_e32 v1, v10, v24
	v_add_f32_e32 v0, v141, v16
	v_mul_f32_e32 v1, 0x3fb8aa3b, v1
	v_add_f32_e32 v0, v142, v0
	v_exp_f32_e32 v151, v1
	v_sub_f32_e32 v1, v11, v24
	v_add_f32_e32 v0, v143, v0
	v_mul_f32_e32 v1, 0x3fb8aa3b, v1
	v_add_f32_e32 v0, v144, v0
	v_exp_f32_e32 v152, v1
	v_sub_f32_e32 v1, v12, v24
	v_add_f32_e32 v0, v145, v0
	v_mul_f32_e32 v1, 0x3fb8aa3b, v1
	v_add_f32_e32 v0, v146, v0
	v_exp_f32_e32 v153, v1
	v_sub_f32_e32 v1, v13, v24
	v_add_f32_e32 v0, v147, v0
	v_mul_f32_e32 v1, 0x3fb8aa3b, v1
	v_add_f32_e32 v0, v148, v0
	v_exp_f32_e32 v154, v1
	v_sub_f32_e32 v1, v14, v24
	v_add_f32_e32 v0, v149, v0
	v_mul_f32_e32 v1, 0x3fb8aa3b, v1
	v_add_f32_e32 v0, v150, v0
	v_exp_f32_e32 v155, v1
	v_sub_f32_e32 v1, v15, v24
	v_add_f32_e32 v0, v151, v0
	v_mul_f32_e32 v1, 0x3fb8aa3b, v1
	v_add_f32_e32 v0, v152, v0
	v_exp_f32_e32 v156, v1
	v_add_f32_e32 v0, v153, v0
	v_add_f32_e32 v0, v154, v0
	v_add_f32_e32 v0, v155, v0
	v_add_f32_e32 v0, v156, v0
	v_mov_b32_e32 v1, v0
	v_mov_b32_e32 v227, v0
	s_nop 1
	v_permlane32_swap_b32_e32 v1, v227
	v_cvt_pk_bf16_f32 v2, v31, v44
	v_add_u32_e32 v44, 0x9000, v136
	ds_read2_b64 v[4:7], v44 offset1:2
	ds_read2_b64 v[36:39], v44 offset0:4 offset1:6
	v_cvt_pk_bf16_f32 v3, v45, v46
	s_waitcnt lgkmcnt(2)
	v_add_f32_e32 v0, v1, v227
	v_sub_f32_e32 v1, v80, v24
	v_mul_f32_e32 v1, 0x3fb8aa3b, v1
	v_exp_f32_e32 v1, v1
	v_add_u32_e32 v45, 0xd000, v136
	v_cvt_pk_bf16_f32 v40, v47, v63
	v_cvt_pk_bf16_f32 v41, v64, v65
	v_add_f32_e32 v34, v1, v0
	v_cvt_pk_bf16_f32 v0, v26, v28
	v_cvt_pk_bf16_f32 v1, v29, v30
	v_cvt_pk_bf16_f32 v42, v66, v67
	v_cvt_pk_bf16_f32 v43, v68, v69
	s_waitcnt lgkmcnt(1)
	v_mfma_f32_32x32x16_bf16 v[16:31], v[4:7], v[0:3], 0
	ds_read2_b64 v[4:7], v45 offset0:96 offset1:98
	s_and_b32 s0, s0, 0xc0
	s_mov_b64 vcc, s[46:47]
	v_readlane_b32 s1, v254, 36
	s_add_i32 s33, s33, 64
	v_mov_b32_e32 v203, 0
	v_lshl_add_u64 v[192:193], s[2:3], 0, v[98:99]
	v_lshlrev_b64 v[192:193], 9, v[192:193]
	v_lshl_add_u64 v[192:193], vcc, 0, v[192:193]
	s_lshl_b32 s2, s0, 1
	v_lshl_add_u64 v[192:193], v[192:193], 0, s[2:3]
	s_and_b32 s0, s38, 4
	s_or_b32 s0, s0, s1
	s_lshr_b32 s0, s0, 2
	v_lshlrev_b32_e32 v202, 1, v100
	v_lshl_add_u64 v[192:193], v[192:193], 0, v[202:203]
	s_mul_i32 s2, s0, 0x4080
	v_lshl_add_u64 v[194:195], s[2:3], 0, v[98:99]
	s_and_b32 s0, s33, 0xc0
	v_or_b32_e32 v196, s0, v134
	v_lshlrev_b64 v[194:195], 9, v[194:195]
	v_lshl_add_u64 v[194:195], vcc, 0, v[194:195]
	v_lshlrev_b32_e32 v202, 1, v196
	v_lshl_add_u64 v[194:195], v[194:195], 0, v[202:203]
	v_lshl_add_u64 v[224:225], v[192:193], 0, v[206:207]
	global_load_dwordx4 v[160:163], v[224:225], off
	global_load_dwordx4 v[164:167], v[224:225], off offset:32
	global_load_dwordx4 v[168:171], v[224:225], off offset:64
	global_load_dwordx4 v[172:175], v[224:225], off offset:96
	global_load_dwordx4 v[176:179], v[194:195], off
	global_load_dwordx4 v[180:183], v[194:195], off offset:32
	global_load_dwordx4 v[184:187], v[194:195], off offset:64
	global_load_dwordx4 v[188:191], v[194:195], off offset:96
	v_rcp_f32_e32 v34, v34
	s_waitcnt lgkmcnt(1)
	v_mfma_f32_32x32x16_bf16 v[16:31], v[36:39], v[40:43], v[16:31]
	ds_read2_b64 v[36:39], v45 offset0:100 offset1:102
	s_waitcnt lgkmcnt(1)
	v_mfma_f32_32x32x16_bf16 v[0:15], v[4:7], v[0:3], 0
	s_waitcnt lgkmcnt(0)
	v_mfma_f32_32x32x16_bf16 v[0:15], v[36:39], v[40:43], v[0:15]
	ds_read2_b64 v[40:43], v44 offset0:8 offset1:10
	v_cvt_pk_bf16_f32 v36, v70, v71
	v_cvt_pk_bf16_f32 v37, v72, v73
	v_cvt_pk_bf16_f32 v38, v74, v75
	v_cvt_pk_bf16_f32 v39, v76, v77
	s_waitcnt lgkmcnt(0)
	s_nop 0
	v_mfma_f32_32x32x16_bf16 v[16:31], v[40:43], v[36:39], v[16:31]
	ds_read2_b64 v[40:43], v45 offset0:104 offset1:106
	s_waitcnt lgkmcnt(0)
	v_mfma_f32_32x32x16_bf16 v[0:15], v[40:43], v[36:39], v[0:15]
	ds_read2_b64 v[40:43], v44 offset0:12 offset1:14
	v_cvt_pk_bf16_f32 v36, v83, v81
	v_cvt_pk_bf16_f32 v37, v82, v78
	v_cvt_pk_bf16_f32 v38, v79, v61
	v_cvt_pk_bf16_f32 v39, v62, v59
	s_waitcnt lgkmcnt(0)
	s_nop 0
	v_mfma_f32_32x32x16_bf16 v[16:31], v[40:43], v[36:39], v[16:31]
	ds_read2_b64 v[40:43], v45 offset0:108 offset1:110
	s_waitcnt lgkmcnt(0)
	v_mfma_f32_32x32x16_bf16 v[0:15], v[40:43], v[36:39], v[0:15]
	ds_read2_b64 v[40:43], v44 offset0:16 offset1:18
	v_cvt_pk_bf16_f32 v36, v60, v57
	v_cvt_pk_bf16_f32 v37, v58, v55
	v_cvt_pk_bf16_f32 v38, v56, v53
	v_cvt_pk_bf16_f32 v39, v54, v52
	s_waitcnt lgkmcnt(0)
	s_nop 0
	v_mfma_f32_32x32x16_bf16 v[16:31], v[40:43], v[36:39], v[16:31]
	ds_read2_b64 v[40:43], v45 offset0:112 offset1:114
	s_waitcnt lgkmcnt(0)
	v_mfma_f32_32x32x16_bf16 v[0:15], v[40:43], v[36:39], v[0:15]
	ds_read2_b64 v[40:43], v44 offset0:20 offset1:22
	v_cvt_pk_bf16_f32 v36, v51, v50
	v_cvt_pk_bf16_f32 v37, v49, v48
	v_cvt_pk_bf16_f32 v38, v84, v85
	v_cvt_pk_bf16_f32 v39, v86, v87
	s_waitcnt lgkmcnt(0)
	s_nop 0
	v_mfma_f32_32x32x16_bf16 v[16:31], v[40:43], v[36:39], v[16:31]
	ds_read2_b64 v[40:43], v45 offset0:116 offset1:118
	s_waitcnt lgkmcnt(0)
	v_mfma_f32_32x32x16_bf16 v[0:15], v[40:43], v[36:39], v[0:15]
	ds_read2_b64 v[40:43], v44 offset0:24 offset1:26
	v_cvt_pk_bf16_f32 v36, v88, v89
	v_cvt_pk_bf16_f32 v37, v90, v91
	v_cvt_pk_bf16_f32 v38, v35, v92
	v_cvt_pk_bf16_f32 v39, v33, v32
	s_waitcnt lgkmcnt(0)
	s_nop 0
	v_mfma_f32_32x32x16_bf16 v[16:31], v[40:43], v[36:39], v[16:31]
	ds_read2_b64 v[40:43], v45 offset0:120 offset1:122
	s_waitcnt lgkmcnt(0)
	v_mfma_f32_32x32x16_bf16 v[0:15], v[40:43], v[36:39], v[0:15]
	ds_read2_b64 v[40:43], v44 offset0:28 offset1:30
	v_cvt_pk_bf16_f32 v36, v93, v94
	v_cvt_pk_bf16_f32 v37, v95, v96
	v_cvt_pk_bf16_f32 v38, v137, v138
	v_cvt_pk_bf16_f32 v39, v139, v140
	s_waitcnt lgkmcnt(0)
	s_nop 0
	v_mfma_f32_32x32x16_bf16 v[16:31], v[40:43], v[36:39], v[16:31]
	ds_read2_b64 v[40:43], v45 offset0:124 offset1:126
	s_waitcnt lgkmcnt(0)
	v_mfma_f32_32x32x16_bf16 v[0:15], v[40:43], v[36:39], v[0:15]
	ds_read2_b64 v[40:43], v44 offset0:32 offset1:34
	v_cvt_pk_bf16_f32 v36, v141, v142
	v_cvt_pk_bf16_f32 v37, v143, v144
	v_cvt_pk_bf16_f32 v38, v145, v146
	v_cvt_pk_bf16_f32 v39, v147, v148
	s_waitcnt lgkmcnt(0)
	s_nop 0
	v_mfma_f32_32x32x16_bf16 v[16:31], v[40:43], v[36:39], v[16:31]
	ds_read2_b64 v[40:43], v45 offset0:128 offset1:130
	s_add_u32 s36, s36, 4
	s_addc_u32 s37, s37, 0
	s_mov_b64 s[0:1], 0x80
	s_cmp_eq_u32 s38, 8
	s_waitcnt lgkmcnt(0)
	v_mfma_f32_32x32x16_bf16 v[0:15], v[40:43], v[36:39], v[0:15]
	ds_read2_b64 v[40:43], v44 offset0:36 offset1:38
	v_cvt_pk_bf16_f32 v36, v149, v150
	v_cvt_pk_bf16_f32 v37, v151, v152
	v_cvt_pk_bf16_f32 v38, v153, v154
	v_cvt_pk_bf16_f32 v39, v155, v156
	s_waitcnt lgkmcnt(0)
	s_nop 0
	v_mfma_f32_32x32x16_bf16 v[16:31], v[40:43], v[36:39], v[16:31]
	ds_read2_b64 v[40:43], v45 offset0:132 offset1:134
	s_waitcnt lgkmcnt(0)
	v_mfma_f32_32x32x16_bf16 v[0:15], v[40:43], v[36:39], v[0:15]
	s_nop 0
	s_nop 0
	s_nop 6
	v_pk_mul_f32 v[16:17], v[16:17], v[34:35] op_sel_hi:[1,0]
	v_pk_mul_f32 v[18:19], v[18:19], v[34:35] op_sel_hi:[1,0]
	s_nop 0
	v_pk_mul_f32 v[0:1], v[0:1], v[34:35] op_sel_hi:[1,0]
	v_pk_mul_f32 v[2:3], v[2:3], v[34:35] op_sel_hi:[1,0]
	v_lshl_add_u64 v[204:205], v[102:103], 0, v[206:207]
	s_waitcnt vmcnt(7)
	s_nop 1
	v_permlane32_swap_b32_e32 v160, v162
	v_permlane32_swap_b32_e32 v161, v163
	v_lshlrev_b32_e32 v50, 16, v160
	v_and_b32_e32 v51, 0xffff0000, v160
	v_lshlrev_b32_e32 v48, 16, v161
	v_and_b32_e32 v49, 0xffff0000, v161
	v_pk_mul_f32 v[16:17], v[16:17], v[50:51]
	v_pk_mul_f32 v[18:19], v[18:19], v[48:49]
	v_cvt_pk_bf16_f32 v208, v16, v17
	v_cvt_pk_bf16_f32 v209, v18, v19
	v_pk_mul_f32 v[16:17], v[20:21], v[34:35] op_sel_hi:[1,0]
	s_waitcnt vmcnt(7)
	v_lshlrev_b32_e32 v18, 16, v162
	v_and_b32_e32 v19, 0xffff0000, v162
	v_pk_mul_f32 v[16:17], v[16:17], v[18:19]
	v_pk_mul_f32 v[18:19], v[22:23], v[34:35] op_sel_hi:[1,0]
	v_lshlrev_b32_e32 v20, 16, v163
	v_and_b32_e32 v21, 0xffff0000, v163
	v_pk_mul_f32 v[18:19], v[18:19], v[20:21]
	v_cvt_pk_bf16_f32 v210, v16, v17
	v_cvt_pk_bf16_f32 v211, v18, v19
	s_nop 1
	v_permlane32_swap_b32_e32 v208, v210
	v_permlane32_swap_b32_e32 v209, v211
	global_store_dwordx4 v[204:205], v[208:211], off offset:-64
	v_pk_mul_f32 v[16:17], v[24:25], v[34:35] op_sel_hi:[1,0]
	s_waitcnt vmcnt(7)
	s_nop 1
	v_permlane32_swap_b32_e32 v164, v166
	v_permlane32_swap_b32_e32 v165, v167
	v_lshlrev_b32_e32 v18, 16, v164
	v_and_b32_e32 v19, 0xffff0000, v164
	v_pk_mul_f32 v[16:17], v[16:17], v[18:19]
	v_pk_mul_f32 v[18:19], v[26:27], v[34:35] op_sel_hi:[1,0]
	v_lshlrev_b32_e32 v20, 16, v165
	v_and_b32_e32 v21, 0xffff0000, v165
	v_pk_mul_f32 v[18:19], v[18:19], v[20:21]
	v_cvt_pk_bf16_f32 v212, v16, v17
	v_cvt_pk_bf16_f32 v213, v18, v19
	v_pk_mul_f32 v[16:17], v[28:29], v[34:35] op_sel_hi:[1,0]
	s_waitcnt vmcnt(7)
	v_lshlrev_b32_e32 v18, 16, v166
	v_and_b32_e32 v19, 0xffff0000, v166
	v_pk_mul_f32 v[16:17], v[16:17], v[18:19]
	v_pk_mul_f32 v[18:19], v[30:31], v[34:35] op_sel_hi:[1,0]
	v_lshlrev_b32_e32 v20, 16, v167
	v_and_b32_e32 v21, 0xffff0000, v167
	v_pk_mul_f32 v[18:19], v[18:19], v[20:21]
	v_cvt_pk_bf16_f32 v214, v16, v17
	v_cvt_pk_bf16_f32 v215, v18, v19
	s_nop 1
	v_permlane32_swap_b32_e32 v212, v214
	v_permlane32_swap_b32_e32 v213, v215
	global_store_dwordx4 v[204:205], v[212:215], off offset:-32
	s_waitcnt vmcnt(7)
	s_nop 1
	v_permlane32_swap_b32_e32 v168, v170
	v_permlane32_swap_b32_e32 v169, v171
	v_lshlrev_b32_e32 v16, 16, v168
	v_and_b32_e32 v17, 0xffff0000, v168
	v_pk_mul_f32 v[0:1], v[0:1], v[16:17]
	v_lshlrev_b32_e32 v16, 16, v169
	v_and_b32_e32 v17, 0xffff0000, v169
	v_pk_mul_f32 v[2:3], v[2:3], v[16:17]
	v_cvt_pk_bf16_f32 v216, v0, v1
	v_cvt_pk_bf16_f32 v217, v2, v3
	v_pk_mul_f32 v[0:1], v[4:5], v[34:35] op_sel_hi:[1,0]
	s_waitcnt vmcnt(7)
	v_lshlrev_b32_e32 v2, 16, v170
	v_and_b32_e32 v3, 0xffff0000, v170
	v_pk_mul_f32 v[0:1], v[0:1], v[2:3]
	v_pk_mul_f32 v[2:3], v[6:7], v[34:35] op_sel_hi:[1,0]
	v_lshlrev_b32_e32 v4, 16, v171
	v_and_b32_e32 v5, 0xffff0000, v171
	v_pk_mul_f32 v[2:3], v[2:3], v[4:5]
	v_cvt_pk_bf16_f32 v218, v0, v1
	v_cvt_pk_bf16_f32 v219, v2, v3
	s_nop 1
	v_permlane32_swap_b32_e32 v216, v218
	v_permlane32_swap_b32_e32 v217, v219
	global_store_dwordx4 v[204:205], v[216:219], off
	v_pk_mul_f32 v[0:1], v[8:9], v[34:35] op_sel_hi:[1,0]
	s_waitcnt vmcnt(7)
	s_nop 1
	v_permlane32_swap_b32_e32 v172, v174
	v_permlane32_swap_b32_e32 v173, v175
	v_lshlrev_b32_e32 v2, 16, v172
	v_and_b32_e32 v3, 0xffff0000, v172
	v_pk_mul_f32 v[0:1], v[0:1], v[2:3]
	v_pk_mul_f32 v[2:3], v[10:11], v[34:35] op_sel_hi:[1,0]
	v_lshlrev_b32_e32 v4, 16, v173
	v_and_b32_e32 v5, 0xffff0000, v173
	v_pk_mul_f32 v[2:3], v[2:3], v[4:5]
	v_cvt_pk_bf16_f32 v220, v0, v1
	v_cvt_pk_bf16_f32 v221, v2, v3
	v_pk_mul_f32 v[0:1], v[12:13], v[34:35] op_sel_hi:[1,0]
	s_waitcnt vmcnt(7)
	v_lshlrev_b32_e32 v2, 16, v174
	v_and_b32_e32 v3, 0xffff0000, v174
	v_pk_mul_f32 v[0:1], v[0:1], v[2:3]
	v_pk_mul_f32 v[2:3], v[14:15], v[34:35] op_sel_hi:[1,0]
	v_lshlrev_b32_e32 v4, 16, v175
	v_and_b32_e32 v5, 0xffff0000, v175
	v_pk_mul_f32 v[2:3], v[2:3], v[4:5]
	v_cvt_pk_bf16_f32 v222, v0, v1
	v_cvt_pk_bf16_f32 v223, v2, v3
	s_nop 1
	v_permlane32_swap_b32_e32 v220, v222
	v_permlane32_swap_b32_e32 v221, v223
	global_store_dwordx4 v[204:205], v[220:223], off offset:32
	v_lshl_add_u64 v[102:103], v[102:103], 0, s[0:1]
	s_waitcnt vmcnt(4)
	v_mov_b32_e32 v80, v176
	v_mov_b32_e32 v81, v177
	v_mov_b32_e32 v82, v178
	v_mov_b32_e32 v83, v179
	v_mov_b32_e32 v84, v180
	v_mov_b32_e32 v85, v181
	v_mov_b32_e32 v86, v182
	v_mov_b32_e32 v87, v183
	v_mov_b32_e32 v88, v184
	v_mov_b32_e32 v89, v185
	v_mov_b32_e32 v90, v186
	v_mov_b32_e32 v91, v187
	v_mov_b32_e32 v92, v188
	v_mov_b32_e32 v93, v189
	v_mov_b32_e32 v94, v190
	v_mov_b32_e32 v95, v191
	s_cbranch_scc0 .LBB0_2056
	v_readlane_b32 s91, v254, 17
	v_readlane_b32 s24, v254, 52
	s_mov_b32 s37, s3
	s_movk_i32 s25, 0x90
	s_branch .LBB0_1999
